# stack (v67) + rotating preload in v192-207 for the merge tile: first 8 gate loads of each K-seam and of the epilogue are issued one stage ahead
# baseline (speedup 1.0000x reference)
; template <class Epi, class Order = StaticOrder, bool HALFN = false>
; __device__ __forceinline__ void gemm_phase(LAS unsigned char* lds, const Gemm g, const Epi& E) {
;     ...
;     f32x4 acc[2][2][4][2];
;     if constexpr (Epi::INIT) E.init(acc, cur, wr, wc, fr, fq);
;     else {
; #pragma unroll
;     for (int a = 0; a < 2; ++a)
; #pragma unroll
;         for (int b = 0; b < 2; ++b)
; #pragma unroll
;             for (int m = 0; m < 4; ++m)
; #pragma unroll
;                 for (int n = 0; n < 2; ++n) acc[a][b][m][n] = (f32x4){0.f, 0.f, 0.f, 0.f};
;     }
;     __device__ __forceinline__ void seam(f32x4 (&acc)[2][2][4][2], const Unit& u, int n, int wr, int wc, int fr, int fq) const {
;     ...
;                 for (int bj = 0; bj < 2; ++bj) { const int row = u.pm * 256 + ai * 128 + wr * 64 + m * 16 + fr, col = u.pn * 256 + bj * 128 + wc * 32 + 8 * fq;
;                     const unsigned char* gp = (const unsigned char*)P + (size_t)row * ROWB + GATE_B0 + n * DM + col; ga[m][bj] = *(const u32x2*)gp; gb[m][bj] = *(const u32x2*)(gp + DM); }
.LBB0_613:
	s_lshl_b32 s8, s27, 8
	s_lshl_b32 s4, s26, 8
	s_or_b32 s42, s4, s21
	s_or_b32 s43, s8, 0x80
	s_add_u32 s4, s52, 0xc0080
	s_addc_u32 s5, s53, 0
	v_mov_b32_e32 v2, v0
	v_mov_b32_e32 v3, v0
	s_add_u32 s62, s54, 0x100
	v_mov_b32_e32 v1, v0
	v_mov_b64_e32 v[6:7], v[2:3]
	v_mov_b64_e32 v[10:11], v[2:3]
	v_mov_b64_e32 v[22:23], v[2:3]
	v_mov_b64_e32 v[26:27], v[2:3]
	v_mov_b64_e32 v[38:39], v[2:3]
	v_mov_b64_e32 v[42:43], v[2:3]
	v_mov_b64_e32 v[54:55], v[2:3]
	v_mov_b64_e32 v[58:59], v[2:3]
	v_mov_b64_e32 v[14:15], v[2:3]
	v_mov_b64_e32 v[18:19], v[2:3]
	v_mov_b64_e32 v[30:31], v[2:3]
	v_mov_b64_e32 v[34:35], v[2:3]
	v_mov_b64_e32 v[46:47], v[2:3]
	v_mov_b64_e32 v[50:51], v[2:3]
	v_mov_b64_e32 v[62:63], v[2:3]
	v_mov_b64_e32 v[66:67], v[2:3]
	v_mov_b64_e32 v[70:71], v[2:3]
	v_mov_b64_e32 v[74:75], v[2:3]
	v_mov_b64_e32 v[86:87], v[2:3]
	v_mov_b64_e32 v[90:91], v[2:3]
	v_mov_b64_e32 v[102:103], v[2:3]
	v_mov_b64_e32 v[106:107], v[2:3]
	v_mov_b64_e32 v[118:119], v[2:3]
	v_mov_b64_e32 v[122:123], v[2:3]
	v_mov_b64_e32 v[78:79], v[2:3]
	v_mov_b64_e32 v[82:83], v[2:3]
	v_mov_b64_e32 v[94:95], v[2:3]
	v_mov_b64_e32 v[98:99], v[2:3]
	v_mov_b64_e32 v[110:111], v[2:3]
	v_mov_b64_e32 v[114:115], v[2:3]
	v_mov_b64_e32 v[126:127], v[2:3]
	v_mov_b64_e32 v[130:131], v[2:3]
	v_lshl_add_u64 v[144:145], s[4:5], 0, v[140:141]
	v_lshl_add_u64 v[146:147], s[4:5], 0, v[142:143]
	s_addc_u32 s63, s55, 0
	s_mov_b32 s74, 0
	s_mov_b64 s[54:55], 0
	v_mov_b64_e32 v[4:5], v[0:1]
	v_mov_b64_e32 v[8:9], v[0:1]
	v_mov_b64_e32 v[20:21], v[0:1]
	v_mov_b64_e32 v[24:25], v[0:1]
	v_mov_b64_e32 v[36:37], v[0:1]
	v_mov_b64_e32 v[40:41], v[0:1]
	v_mov_b64_e32 v[52:53], v[0:1]
	v_mov_b64_e32 v[56:57], v[0:1]
	v_mov_b64_e32 v[12:13], v[0:1]
	v_mov_b64_e32 v[16:17], v[0:1]
	v_mov_b64_e32 v[28:29], v[0:1]
	v_mov_b64_e32 v[32:33], v[0:1]
	v_mov_b64_e32 v[44:45], v[0:1]
	v_mov_b64_e32 v[48:49], v[0:1]
	v_mov_b64_e32 v[60:61], v[0:1]
	v_mov_b64_e32 v[64:65], v[0:1]
	v_mov_b64_e32 v[68:69], v[0:1]
	v_mov_b64_e32 v[72:73], v[0:1]
	v_mov_b64_e32 v[84:85], v[0:1]
	v_mov_b64_e32 v[88:89], v[0:1]
	v_mov_b64_e32 v[100:101], v[0:1]
	v_mov_b64_e32 v[104:105], v[0:1]
	v_mov_b64_e32 v[116:117], v[0:1]
	v_mov_b64_e32 v[120:121], v[0:1]
	v_mov_b64_e32 v[76:77], v[0:1]
	v_mov_b64_e32 v[80:81], v[0:1]
	v_mov_b64_e32 v[92:93], v[0:1]
	v_mov_b64_e32 v[96:97], v[0:1]
	v_mov_b64_e32 v[108:109], v[0:1]
	v_mov_b64_e32 v[112:113], v[0:1]
	v_mov_b64_e32 v[124:125], v[0:1]
	v_mov_b64_e32 v[128:129], v[0:1]
	s_and_b32 s99, s42, 32
	s_lshl_b32 s99, s99, 4
	v_lshl_add_u32 v254, v181, 7, s99
	v_lshl_add_u32 v254, v180, 3, v254
	s_lshr_b32 s98, s42, 7
	s_bfe_u32 s99, s42, 0x10006
	s_or_b32 s98, s98, s99
	s_add_i32 s98, s98, s8
	s_add_i32 s98, s98, s20
	s_mul_i32 s98, s98, 0x4800
	s_add_u32 s98, s68, s98
	s_addc_u32 s99, s69, 0
	s_add_u32 s98, s98, 0x3000
	s_addc_u32 s99, s99, 0
	global_load_dwordx2 v[192:193], v254, s[98:99] offset:2048
	global_load_dwordx2 v[194:195], v254, s[98:99]
	global_load_dwordx2 v[196:197], v254, s[98:99] offset:3072
	global_load_dwordx2 v[198:199], v254, s[98:99] offset:1024
	s_add_u32 s98, s98, 0x48000
	s_addc_u32 s99, s99, 0
	global_load_dwordx2 v[200:201], v254, s[98:99] offset:2048
	global_load_dwordx2 v[202:203], v254, s[98:99]
	global_load_dwordx2 v[204:205], v254, s[98:99] offset:3072
	global_load_dwordx2 v[206:207], v254, s[98:99] offset:1024
	s_cmp_lt_i32 s74, 32
	s_cbranch_scc1 .LBB0_615

; __device__ __forceinline__ f32x4 un_unorm8(unsigned w) { return (f32x4){fmaxf((float)(w & 255u), 0.5f), fmaxf((float)((w >> 8) & 255u), 0.5f), fmaxf((float)((w >> 16) & 255u), 0.5f), fmaxf((float)(w >> 24), 0.5f)}; }
; #define EPI_OPAQUE asm volatile("" : "+v"(fr), "+v"(fq));
;     __device__ __forceinline__ void seam(f32x4 (&acc)[2][2][4][2], const Unit& u, int n, int wr, int wc, int fr, int fq) const {
;         EPI_OPAQUE
; #pragma unroll
;         for (int ai = 0; ai < 2; ++ai) {
;             u32x2 ga[4][2], gb[4][2];
; #pragma unroll
;             for (int m = 0; m < 4; ++m)
; #pragma unroll
;                 for (int bj = 0; bj < 2; ++bj) { const int row = u.pm * 256 + ai * 128 + wr * 64 + m * 16 + fr, col = u.pn * 256 + bj * 128 + wc * 32 + 8 * fq;
;                     const unsigned char* gp = (const unsigned char*)P + (size_t)row * ROWB + GATE_B0 + n * DM + col; ga[m][bj] = *(const u32x2*)gp; gb[m][bj] = *(const u32x2*)(gp + DM); }
; #pragma unroll
;             for (int m = 0; m < 4; ++m)
; #pragma unroll
;                 for (int bj = 0; bj < 2; ++bj) { const f32x4 a0 = un_unorm8(ga[m][bj].x), a1 = un_unorm8(ga[m][bj].y), b0 = un_unorm8(gb[m][bj].x), b1 = un_unorm8(gb[m][bj].y);
; #pragma unroll
;                     for (int j = 0; j < 4; ++j) { acc[ai][bj][m][0][j] *= a0[j] * __builtin_amdgcn_rcpf(b0[j]); acc[ai][bj][m][1][j] *= a1[j] * __builtin_amdgcn_rcpf(b1[j]); } }
.LBB0_617:
	s_andn2_b64 vcc, exec, s[4:5]
	s_cbranch_vccnz .LBB0_619
	s_lshr_b32 s98, s42, 7
	s_bfe_u32 s99, s42, 0x10006
	s_or_b32 s98, s98, s99
	v_mov_b32_e32 v1, s98
	v_mov_b32_e32 v2, v181
	s_cmpk_eq_i32 s54, 0x800
	v_add_u32_e32 v1, s20, v1
	v_add_u32_e32 v154, s8, v1
	v_mov_b64_e32 v[148:149], s[68:69]
	s_cselect_b32 s56, 0, 0x800
	s_and_b32 s99, s42, 32
	s_lshl_b32 s99, s99, 4
	v_lshl_add_u32 v2, v2, 7, s99
	v_lshl_add_u32 v2, v180, 3, v2
	v_mad_i64_i32 v[150:151], s[4:5], v154, s33, v[148:149]
	v_ashrrev_i32_e32 v3, 31, v2
	v_lshl_add_u64 v[150:151], v[150:151], 0, s[56:57]
	v_lshl_add_u64 v[150:151], v[150:151], 0, v[2:3]
	v_lshl_add_u64 v[152:153], v[150:151], 0, s[64:65]
	v_add_co_u32_e32 v150, vcc, s12, v150
	s_nop 0
	v_addc_co_u32_e32 v151, vcc, 0, v151, vcc
	v_add_u32_e32 v150, 16, v154
	v_add_u32_e32 v156, 48, v154
	v_mad_i64_i32 v[150:151], s[4:5], v150, s33, v[148:149]
	v_mad_i64_i32 v[156:157], s[4:5], v156, s33, v[148:149]
	v_lshl_add_u64 v[150:151], v[150:151], 0, s[56:57]
	v_lshl_add_u64 v[156:157], v[156:157], 0, s[56:57]
	v_lshl_add_u64 v[150:151], v[150:151], 0, v[2:3]
	v_lshl_add_u64 v[152:153], v[156:157], 0, v[2:3]
	v_lshl_add_u64 v[156:157], v[150:151], 0, s[64:65]
	v_add_co_u32_e32 v150, vcc, s12, v150
	v_add_u32_e32 v155, 32, v154
	s_nop 0
	v_addc_co_u32_e32 v151, vcc, 0, v151, vcc
	v_mad_i64_i32 v[154:155], s[4:5], v155, s33, v[148:149]
	v_lshl_add_u64 v[154:155], v[154:155], 0, s[56:57]
	v_lshl_add_u64 v[154:155], v[154:155], 0, v[2:3]
	v_lshl_add_u64 v[160:161], v[154:155], 0, s[64:65]
	v_add_co_u32_e32 v154, vcc, s12, v154
	v_lshl_add_u64 v[212:213], v[152:153], 0, s[64:65]
	s_nop 0
	v_addc_co_u32_e32 v155, vcc, 0, v155, vcc
	global_load_dwordx2 v[168:169], v[160:161], off offset:2048
	global_load_dwordx2 v[170:171], v[154:155], off
	global_load_dwordx2 v[158:159], v[160:161], off offset:3072
	s_nop 0
	global_load_dwordx2 v[160:161], v[160:161], off offset:1024
	v_add_co_u32_e32 v150, vcc, s12, v152
	v_add_u32_e32 v1, s43, v1
	s_nop 0
	v_addc_co_u32_e32 v151, vcc, 0, v153, vcc
	global_load_dwordx2 v[154:155], v[212:213], off offset:2048
	global_load_dwordx2 v[156:157], v[150:151], off
	s_nop 0
	global_load_dwordx2 v[150:151], v[212:213], off offset:3072
	global_load_dwordx2 v[152:153], v[212:213], off offset:1024
	s_and_b64 vcc, exec, s[46:47]
	s_cbranch_vccz .Lsm_a
	s_barrier
.Lsm_a:
	v_cvt_f32_ubyte0_e32 v212, v192
	v_cvt_f32_ubyte1_e32 v213, v192
	v_cvt_f32_ubyte2_e32 v214, v192
	v_cvt_f32_ubyte0_e32 v219, v195
	v_cvt_f32_ubyte3_e32 v184, v192
	v_cvt_f32_ubyte3_e32 v218, v194
	v_max_f32_e32 v225, 0.5, v214
	v_max_f32_e32 v214, 0.5, v219
	v_max_f32_e32 v219, 0.5, v184
	v_cvt_f32_ubyte0_e32 v184, v193
	v_cvt_f32_ubyte2_e32 v217, v194
	v_cvt_f32_ubyte3_e32 v222, v195
	v_max_f32_e32 v224, 0.5, v213
	v_max_f32_e32 v213, 0.5, v218
	v_max_f32_e32 v218, 0.5, v184
	v_cvt_f32_ubyte1_e32 v184, v193
	v_max_f32_e32 v223, 0.5, v212
	v_max_f32_e32 v212, 0.5, v217
	v_max_f32_e32 v217, 0.5, v222
	v_max_f32_e32 v222, 0.5, v184
	v_cvt_f32_ubyte2_e32 v184, v193
	v_cvt_f32_ubyte0_e32 v215, v194
	v_cvt_f32_ubyte1_e32 v216, v194
	v_cvt_f32_ubyte1_e32 v220, v195
	v_cvt_f32_ubyte2_e32 v221, v195
	v_max_f32_e32 v226, 0.5, v184
	v_cvt_f32_ubyte3_e32 v184, v193
	v_max_f32_e32 v186, 0.5, v215
	v_max_f32_e32 v187, 0.5, v216
	v_max_f32_e32 v215, 0.5, v220
	v_max_f32_e32 v216, 0.5, v221
	v_max_f32_e32 v227, 0.5, v184
	v_rcp_f32_e32 v184, v223
	v_rcp_f32_e32 v185, v224
	v_rcp_f32_e32 v220, v225
	v_rcp_f32_e32 v221, v219
	v_rcp_f32_e32 v218, v218
	v_rcp_f32_e32 v219, v222
	v_rcp_f32_e32 v222, v226
	v_rcp_f32_e32 v223, v227
	v_pk_mul_f32 v[184:185], v[186:187], v[184:185]
	v_pk_mul_f32 v[186:187], v[212:213], v[220:221]
	v_pk_mul_f32 v[128:129], v[128:129], v[184:185]
	v_pk_mul_f32 v[130:131], v[130:131], v[186:187]
	v_pk_mul_f32 v[184:185], v[214:215], v[218:219]
	v_pk_mul_f32 v[186:187], v[216:217], v[222:223]
	v_cvt_f32_ubyte0_e32 v214, v196
	v_cvt_f32_ubyte1_e32 v215, v196
	v_cvt_f32_ubyte2_e32 v216, v196
	v_cvt_f32_ubyte3_e32 v208, v196
	v_max_f32_e32 v217, 0.5, v208
	v_cvt_f32_ubyte0_e32 v208, v197
	v_max_f32_e32 v218, 0.5, v208
	v_cvt_f32_ubyte1_e32 v208, v197
	v_max_f32_e32 v219, 0.5, v208
	v_cvt_f32_ubyte2_e32 v208, v197
	v_max_f32_e32 v214, 0.5, v214
	v_max_f32_e32 v215, 0.5, v215
	v_max_f32_e32 v216, 0.5, v216
	v_max_f32_e32 v220, 0.5, v208
	v_cvt_f32_ubyte3_e32 v208, v197
	v_max_f32_e32 v221, 0.5, v208
	v_rcp_f32_e32 v208, v214
	v_rcp_f32_e32 v209, v215
	v_rcp_f32_e32 v216, v216
	v_rcp_f32_e32 v217, v217
	v_pk_mul_f32 v[126:127], v[126:127], v[186:187]
	v_pk_mul_f32 v[124:125], v[124:125], v[184:185]
	v_cvt_f32_ubyte0_e32 v184, v198
	v_cvt_f32_ubyte1_e32 v185, v198
	v_cvt_f32_ubyte2_e32 v186, v198
	v_cvt_f32_ubyte3_e32 v187, v198
	v_cvt_f32_ubyte0_e32 v210, v199
	v_rcp_f32_e32 v214, v218
	v_rcp_f32_e32 v215, v219
	v_rcp_f32_e32 v218, v220
	v_rcp_f32_e32 v219, v221
	v_max_f32_e32 v212, 0.5, v210
	v_cvt_f32_ubyte1_e32 v210, v199
	v_max_f32_e32 v184, 0.5, v184
	v_max_f32_e32 v185, 0.5, v185
	v_max_f32_e32 v186, 0.5, v186
	v_max_f32_e32 v187, 0.5, v187
	v_max_f32_e32 v213, 0.5, v210
	v_cvt_f32_ubyte2_e32 v210, v199
	v_cvt_f32_ubyte3_e32 v211, v199
	v_max_f32_e32 v210, 0.5, v210
	v_max_f32_e32 v211, 0.5, v211
	v_pk_mul_f32 v[184:185], v[184:185], v[208:209]
	v_pk_mul_f32 v[186:187], v[186:187], v[216:217]
	v_pk_mul_f32 v[120:121], v[120:121], v[184:185]
	v_pk_mul_f32 v[122:123], v[122:123], v[186:187]
	v_pk_mul_f32 v[184:185], v[212:213], v[214:215]
	v_pk_mul_f32 v[186:187], v[210:211], v[218:219]
	v_cvt_f32_ubyte0_e32 v210, v200
	v_cvt_f32_ubyte1_e32 v211, v200
	v_cvt_f32_ubyte2_e32 v212, v200
	v_cvt_f32_ubyte3_e32 v176, v200
; __device__ __forceinline__ f32x4 un_unorm8(unsigned w) { return (f32x4){fmaxf((float)(w & 255u), 0.5f), fmaxf((float)((w >> 8) & 255u), 0.5f), fmaxf((float)((w >> 16) & 255u), 0.5f), fmaxf((float)(w >> 24), 0.5f)}; }
;     __device__ __forceinline__ void seam(f32x4 (&acc)[2][2][4][2], const Unit& u, int n, int wr, int wc, int fr, int fq) const {
;     ...
;             for (int m = 0; m < 4; ++m)
; #pragma unroll
;                 for (int bj = 0; bj < 2; ++bj) { const f32x4 a0 = un_unorm8(ga[m][bj].x), a1 = un_unorm8(ga[m][bj].y), b0 = un_unorm8(gb[m][bj].x), b1 = un_unorm8(gb[m][bj].y);
; #pragma unroll
;                     for (int j = 0; j < 4; ++j) { acc[ai][bj][m][0][j] *= a0[j] * __builtin_amdgcn_rcpf(b0[j]); acc[ai][bj][m][1][j] *= a1[j] * __builtin_amdgcn_rcpf(b1[j]); } }
	v_max_f32_e32 v213, 0.5, v176
	v_cvt_f32_ubyte0_e32 v176, v201
	v_max_f32_e32 v214, 0.5, v176
	v_cvt_f32_ubyte1_e32 v176, v201
	v_max_f32_e32 v215, 0.5, v176
	v_cvt_f32_ubyte2_e32 v176, v201
	v_max_f32_e32 v210, 0.5, v210
	v_max_f32_e32 v211, 0.5, v211
	v_max_f32_e32 v216, 0.5, v176
	v_cvt_f32_ubyte3_e32 v176, v201
	v_max_f32_e32 v212, 0.5, v212
	v_max_f32_e32 v217, 0.5, v176
	v_rcp_f32_e32 v176, v210
	v_rcp_f32_e32 v177, v211
	v_pk_mul_f32 v[118:119], v[118:119], v[186:187]
	v_pk_mul_f32 v[116:117], v[116:117], v[184:185]
	v_cvt_f32_ubyte0_e32 v184, v202
	v_cvt_f32_ubyte1_e32 v185, v202
	v_cvt_f32_ubyte2_e32 v186, v202
	v_cvt_f32_ubyte3_e32 v178, v202
	v_rcp_f32_e32 v210, v214
	v_rcp_f32_e32 v212, v212
	v_rcp_f32_e32 v213, v213
	v_rcp_f32_e32 v211, v215
	v_max_f32_e32 v187, 0.5, v178
	v_cvt_f32_ubyte0_e32 v178, v203
	v_max_f32_e32 v184, 0.5, v184
	v_max_f32_e32 v185, 0.5, v185
	v_max_f32_e32 v208, 0.5, v178
	v_cvt_f32_ubyte1_e32 v178, v203
	v_max_f32_e32 v186, 0.5, v186
	v_max_f32_e32 v209, 0.5, v178
	v_pk_mul_f32 v[176:177], v[184:185], v[176:177]
	v_pk_mul_f32 v[184:185], v[186:187], v[212:213]
	v_pk_mul_f32 v[112:113], v[112:113], v[176:177]
	v_pk_mul_f32 v[176:177], v[208:209], v[210:211]
	v_cvt_f32_ubyte0_e32 v186, v204
	v_cvt_f32_ubyte1_e32 v187, v204
	v_cvt_f32_ubyte2_e32 v208, v204
	v_cvt_f32_ubyte3_e32 v172, v204
	v_rcp_f32_e32 v214, v216
	v_rcp_f32_e32 v215, v217
	v_max_f32_e32 v209, 0.5, v172
	v_cvt_f32_ubyte0_e32 v172, v205
	v_max_f32_e32 v210, 0.5, v172
	v_cvt_f32_ubyte1_e32 v172, v205
	v_cvt_f32_ubyte2_e32 v178, v203
	v_cvt_f32_ubyte3_e32 v179, v203
	v_max_f32_e32 v211, 0.5, v172
	v_cvt_f32_ubyte2_e32 v172, v205
	v_max_f32_e32 v178, 0.5, v178
	v_max_f32_e32 v179, 0.5, v179
	v_max_f32_e32 v186, 0.5, v186
	v_max_f32_e32 v187, 0.5, v187
	v_max_f32_e32 v212, 0.5, v172
	v_cvt_f32_ubyte3_e32 v172, v205
	v_pk_mul_f32 v[178:179], v[178:179], v[214:215]
	v_max_f32_e32 v208, 0.5, v208
	v_max_f32_e32 v213, 0.5, v172
	v_rcp_f32_e32 v172, v186
	v_rcp_f32_e32 v173, v187
	v_pk_mul_f32 v[110:111], v[110:111], v[178:179]
	v_pk_mul_f32 v[108:109], v[108:109], v[176:177]
	v_cvt_f32_ubyte0_e32 v176, v206
	v_cvt_f32_ubyte1_e32 v177, v206
	v_cvt_f32_ubyte2_e32 v178, v206
	v_cvt_f32_ubyte3_e32 v174, v206
	v_rcp_f32_e32 v186, v210
	v_rcp_f32_e32 v208, v208
	v_rcp_f32_e32 v209, v209
	v_rcp_f32_e32 v187, v211
	v_max_f32_e32 v179, 0.5, v174
	v_cvt_f32_ubyte0_e32 v174, v207
	v_pk_mul_f32 v[114:115], v[114:115], v[184:185]
	v_max_f32_e32 v176, 0.5, v176
	v_max_f32_e32 v177, 0.5, v177
	v_max_f32_e32 v184, 0.5, v174
	v_cvt_f32_ubyte1_e32 v174, v207
	v_max_f32_e32 v178, 0.5, v178
	v_max_f32_e32 v185, 0.5, v174
	v_pk_mul_f32 v[172:173], v[176:177], v[172:173]
	v_pk_mul_f32 v[176:177], v[178:179], v[208:209]
	v_pk_mul_f32 v[104:105], v[104:105], v[172:173]
	v_pk_mul_f32 v[172:173], v[184:185], v[186:187]
	s_waitcnt vmcnt(0)
	v_cvt_f32_ubyte0_e32 v178, v168
	v_cvt_f32_ubyte1_e32 v179, v168
	v_cvt_f32_ubyte2_e32 v184, v168
	v_cvt_f32_ubyte3_e32 v168, v168
	v_rcp_f32_e32 v210, v212
	v_rcp_f32_e32 v211, v213
	v_max_f32_e32 v185, 0.5, v168
	v_cvt_f32_ubyte0_e32 v168, v169
	v_max_f32_e32 v186, 0.5, v168
	v_cvt_f32_ubyte1_e32 v168, v169
	v_cvt_f32_ubyte2_e32 v174, v207
	v_cvt_f32_ubyte3_e32 v175, v207
	v_max_f32_e32 v187, 0.5, v168
	v_cvt_f32_ubyte2_e32 v168, v169
	v_max_f32_e32 v174, 0.5, v174
	v_max_f32_e32 v175, 0.5, v175
	v_max_f32_e32 v178, 0.5, v178
	v_max_f32_e32 v179, 0.5, v179
	v_max_f32_e32 v208, 0.5, v168
	v_cvt_f32_ubyte3_e32 v168, v169
	v_pk_mul_f32 v[174:175], v[174:175], v[210:211]
	v_max_f32_e32 v184, 0.5, v184
	v_max_f32_e32 v209, 0.5, v168
	v_rcp_f32_e32 v168, v178
	v_rcp_f32_e32 v169, v179
	v_pk_mul_f32 v[102:103], v[102:103], v[174:175]
	v_pk_mul_f32 v[100:101], v[100:101], v[172:173]
	v_cvt_f32_ubyte0_e32 v172, v170
	v_cvt_f32_ubyte1_e32 v173, v170
	v_cvt_f32_ubyte2_e32 v174, v170
	v_cvt_f32_ubyte3_e32 v170, v170
	v_rcp_f32_e32 v178, v186
	v_rcp_f32_e32 v184, v184
	v_rcp_f32_e32 v185, v185
	v_rcp_f32_e32 v179, v187
	v_max_f32_e32 v175, 0.5, v170
	v_cvt_f32_ubyte0_e32 v170, v171
	v_pk_mul_f32 v[106:107], v[106:107], v[176:177]
	v_max_f32_e32 v172, 0.5, v172
	v_max_f32_e32 v173, 0.5, v173
	v_max_f32_e32 v176, 0.5, v170
	v_cvt_f32_ubyte1_e32 v170, v171
	v_max_f32_e32 v174, 0.5, v174
	v_max_f32_e32 v177, 0.5, v170
	v_pk_mul_f32 v[168:169], v[172:173], v[168:169]
	v_pk_mul_f32 v[172:173], v[174:175], v[184:185]
	v_pk_mul_f32 v[96:97], v[96:97], v[168:169]
	v_pk_mul_f32 v[168:169], v[176:177], v[178:179]
	v_cvt_f32_ubyte0_e32 v174, v158
	v_cvt_f32_ubyte1_e32 v175, v158
	v_cvt_f32_ubyte2_e32 v176, v158
	v_cvt_f32_ubyte3_e32 v158, v158
	v_rcp_f32_e32 v186, v208
	v_rcp_f32_e32 v187, v209
	v_max_f32_e32 v177, 0.5, v158
	v_cvt_f32_ubyte0_e32 v158, v159
	v_max_f32_e32 v178, 0.5, v158
	v_cvt_f32_ubyte1_e32 v158, v159
	v_cvt_f32_ubyte2_e32 v170, v171
	v_cvt_f32_ubyte3_e32 v171, v171
	v_max_f32_e32 v179, 0.5, v158
	v_cvt_f32_ubyte2_e32 v158, v159
	v_max_f32_e32 v170, 0.5, v170
	v_max_f32_e32 v171, 0.5, v171
	v_max_f32_e32 v174, 0.5, v174
	v_max_f32_e32 v175, 0.5, v175
	v_max_f32_e32 v184, 0.5, v158
	v_cvt_f32_ubyte3_e32 v158, v159
	v_pk_mul_f32 v[170:171], v[170:171], v[186:187]
	v_max_f32_e32 v176, 0.5, v176
	v_max_f32_e32 v185, 0.5, v158
	v_rcp_f32_e32 v158, v174
	v_rcp_f32_e32 v159, v175
	v_pk_mul_f32 v[94:95], v[94:95], v[170:171]
	v_pk_mul_f32 v[92:93], v[92:93], v[168:169]
	v_cvt_f32_ubyte0_e32 v168, v160
	v_cvt_f32_ubyte1_e32 v169, v160
	v_cvt_f32_ubyte2_e32 v170, v160
	v_cvt_f32_ubyte3_e32 v160, v160
	v_rcp_f32_e32 v174, v178
	v_rcp_f32_e32 v176, v176
	v_rcp_f32_e32 v177, v177
	v_rcp_f32_e32 v175, v179
	v_max_f32_e32 v171, 0.5, v160
; __device__ __forceinline__ f32x4 un_unorm8(unsigned w) { return (f32x4){fmaxf((float)(w & 255u), 0.5f), fmaxf((float)((w >> 8) & 255u), 0.5f), fmaxf((float)((w >> 16) & 255u), 0.5f), fmaxf((float)(w >> 24), 0.5f)}; }
;     __device__ __forceinline__ void seam(f32x4 (&acc)[2][2][4][2], const Unit& u, int n, int wr, int wc, int fr, int fq) const {
;     ...
;         for (int ai = 0; ai < 2; ++ai) {
;             u32x2 ga[4][2], gb[4][2];
; #pragma unroll
;             for (int m = 0; m < 4; ++m)
; #pragma unroll
;                 for (int bj = 0; bj < 2; ++bj) { const int row = u.pm * 256 + ai * 128 + wr * 64 + m * 16 + fr, col = u.pn * 256 + bj * 128 + wc * 32 + 8 * fq;
;                     const unsigned char* gp = (const unsigned char*)P + (size_t)row * ROWB + GATE_B0 + n * DM + col; ga[m][bj] = *(const u32x2*)gp; gb[m][bj] = *(const u32x2*)(gp + DM); }
; #pragma unroll
;             for (int m = 0; m < 4; ++m)
; #pragma unroll
;                 for (int bj = 0; bj < 2; ++bj) { const f32x4 a0 = un_unorm8(ga[m][bj].x), a1 = un_unorm8(ga[m][bj].y), b0 = un_unorm8(gb[m][bj].x), b1 = un_unorm8(gb[m][bj].y);
; #pragma unroll
;                     for (int j = 0; j < 4; ++j) { acc[ai][bj][m][0][j] *= a0[j] * __builtin_amdgcn_rcpf(b0[j]); acc[ai][bj][m][1][j] *= a1[j] * __builtin_amdgcn_rcpf(b1[j]); } }
;             asm volatile("" ::: "memory");
	v_cvt_f32_ubyte0_e32 v160, v161
	v_pk_mul_f32 v[98:99], v[98:99], v[172:173]
	v_max_f32_e32 v168, 0.5, v168
	v_max_f32_e32 v169, 0.5, v169
	v_max_f32_e32 v172, 0.5, v160
	v_cvt_f32_ubyte1_e32 v160, v161
	v_max_f32_e32 v170, 0.5, v170
	v_max_f32_e32 v173, 0.5, v160
	v_pk_mul_f32 v[158:159], v[168:169], v[158:159]
	v_pk_mul_f32 v[168:169], v[170:171], v[176:177]
	v_pk_mul_f32 v[88:89], v[88:89], v[158:159]
	v_pk_mul_f32 v[158:159], v[172:173], v[174:175]
	v_cvt_f32_ubyte0_e32 v170, v154
	v_cvt_f32_ubyte1_e32 v171, v154
	v_cvt_f32_ubyte2_e32 v172, v154
	v_cvt_f32_ubyte3_e32 v154, v154
	v_max_f32_e32 v173, 0.5, v154
	v_cvt_f32_ubyte0_e32 v154, v155
	v_rcp_f32_e32 v178, v184
	v_rcp_f32_e32 v179, v185
	v_max_f32_e32 v174, 0.5, v154
	v_cvt_f32_ubyte1_e32 v154, v155
	v_max_f32_e32 v175, 0.5, v154
	v_cvt_f32_ubyte2_e32 v154, v155
	v_cvt_f32_ubyte2_e32 v160, v161
	v_cvt_f32_ubyte3_e32 v161, v161
	v_max_f32_e32 v170, 0.5, v170
	v_max_f32_e32 v171, 0.5, v171
	v_max_f32_e32 v172, 0.5, v172
	v_max_f32_e32 v176, 0.5, v154
	v_cvt_f32_ubyte3_e32 v154, v155
	v_max_f32_e32 v160, 0.5, v160
	v_max_f32_e32 v161, 0.5, v161
	v_max_f32_e32 v177, 0.5, v154
	v_rcp_f32_e32 v154, v170
	v_rcp_f32_e32 v155, v171
	v_rcp_f32_e32 v172, v172
	v_rcp_f32_e32 v173, v173
	v_pk_mul_f32 v[160:161], v[160:161], v[178:179]
	v_pk_mul_f32 v[84:85], v[84:85], v[158:159]
	v_pk_mul_f32 v[86:87], v[86:87], v[160:161]
	v_cvt_f32_ubyte0_e32 v158, v156
	v_cvt_f32_ubyte1_e32 v159, v156
	v_cvt_f32_ubyte2_e32 v160, v156
	v_cvt_f32_ubyte3_e32 v156, v156
	v_max_f32_e32 v158, 0.5, v158
	v_max_f32_e32 v159, 0.5, v159
	v_max_f32_e32 v160, 0.5, v160
	v_max_f32_e32 v161, 0.5, v156
	v_rcp_f32_e32 v170, v174
	v_rcp_f32_e32 v171, v175
	v_cvt_f32_ubyte0_e32 v156, v157
	v_pk_mul_f32 v[154:155], v[158:159], v[154:155]
	v_pk_mul_f32 v[158:159], v[160:161], v[172:173]
	v_mad_i64_i32 v[160:161], s[4:5], v1, s33, v[148:149]
	v_pk_mul_f32 v[90:91], v[90:91], v[168:169]
	v_max_f32_e32 v168, 0.5, v156
	v_cvt_f32_ubyte1_e32 v156, v157
	v_lshl_add_u64 v[160:161], v[160:161], 0, s[56:57]
	v_max_f32_e32 v169, 0.5, v156
	v_lshl_add_u64 v[160:161], v[160:161], 0, v[2:3]
	v_pk_mul_f32 v[80:81], v[80:81], v[154:155]
	v_pk_mul_f32 v[154:155], v[168:169], v[170:171]
	v_add_co_u32_e32 v168, vcc, s12, v160
	v_rcp_f32_e32 v174, v176
	s_nop 0
	v_addc_co_u32_e32 v169, vcc, 0, v161, vcc
	global_load_dwordx2 v[172:173], v[168:169], off
	v_rcp_f32_e32 v175, v177
	v_cvt_f32_ubyte2_e32 v156, v157
	v_cvt_f32_ubyte3_e32 v157, v157
	v_max_f32_e32 v156, 0.5, v156
	v_max_f32_e32 v157, 0.5, v157
	v_lshl_add_u64 v[160:161], v[160:161], 0, s[64:65]
	v_pk_mul_f32 v[156:157], v[156:157], v[174:175]
	global_load_dwordx2 v[174:175], v[160:161], off offset:2048
	v_cvt_f32_ubyte0_e32 v168, v150
	v_cvt_f32_ubyte1_e32 v169, v150
	v_cvt_f32_ubyte2_e32 v170, v150
	v_cvt_f32_ubyte3_e32 v150, v150
	v_max_f32_e32 v171, 0.5, v150
	v_cvt_f32_ubyte0_e32 v150, v151
	v_max_f32_e32 v176, 0.5, v150
	v_cvt_f32_ubyte1_e32 v150, v151
	v_max_f32_e32 v177, 0.5, v150
	v_cvt_f32_ubyte2_e32 v150, v151
	v_max_f32_e32 v178, 0.5, v150
	v_cvt_f32_ubyte3_e32 v150, v151
	v_pk_mul_f32 v[78:79], v[78:79], v[156:157]
	v_pk_mul_f32 v[76:77], v[76:77], v[154:155]
	v_cvt_f32_ubyte0_e32 v154, v152
	v_cvt_f32_ubyte1_e32 v155, v152
	v_cvt_f32_ubyte2_e32 v156, v152
	v_cvt_f32_ubyte3_e32 v152, v152
	v_max_f32_e32 v168, 0.5, v168
	v_max_f32_e32 v169, 0.5, v169
	v_max_f32_e32 v179, 0.5, v150
	v_max_f32_e32 v157, 0.5, v152
	v_cvt_f32_ubyte0_e32 v152, v153
	v_rcp_f32_e32 v150, v168
	v_rcp_f32_e32 v168, v176
	v_rcp_f32_e32 v151, v169
	v_rcp_f32_e32 v169, v177
	v_rcp_f32_e32 v176, v178
	v_rcp_f32_e32 v177, v179
	v_pk_mul_f32 v[82:83], v[82:83], v[158:159]
	v_max_f32_e32 v158, 0.5, v152
	v_cvt_f32_ubyte1_e32 v152, v153
	v_max_f32_e32 v159, 0.5, v152
	v_cvt_f32_ubyte2_e32 v152, v153
	v_cvt_f32_ubyte3_e32 v153, v153
	v_max_f32_e32 v152, 0.5, v152
	v_max_f32_e32 v153, 0.5, v153
	v_pk_mul_f32 v[152:153], v[152:153], v[176:177]
	global_load_dwordx2 v[176:177], v[160:161], off offset:3072
	global_load_dwordx2 v[178:179], v[160:161], off offset:1024
	v_max_f32_e32 v154, 0.5, v154
	v_max_f32_e32 v155, 0.5, v155
	v_pk_mul_f32 v[150:151], v[154:155], v[150:151]
	v_max_f32_e32 v170, 0.5, v170
	v_pk_mul_f32 v[72:73], v[72:73], v[150:151]
	v_pk_mul_f32 v[150:151], v[158:159], v[168:169]
	v_rcp_f32_e32 v170, v170
	v_pk_mul_f32 v[68:69], v[68:69], v[150:151]
	v_add_u32_e32 v150, 16, v1
	v_mad_i64_i32 v[150:151], s[4:5], v150, s33, v[148:149]
	v_rcp_f32_e32 v171, v171
	v_lshl_add_u64 v[150:151], v[150:151], 0, s[56:57]
	v_lshl_add_u64 v[150:151], v[150:151], 0, v[2:3]
	v_pk_mul_f32 v[70:71], v[70:71], v[152:153]
	v_lshl_add_u64 v[152:153], v[150:151], 0, s[64:65]
	v_add_co_u32_e32 v150, vcc, s12, v150
	v_max_f32_e32 v156, 0.5, v156
	s_nop 0
	v_addc_co_u32_e32 v151, vcc, 0, v151, vcc
	v_pk_mul_f32 v[154:155], v[156:157], v[170:171]
	global_load_dwordx2 v[184:185], v[150:151], off
	global_load_dwordx2 v[186:187], v[152:153], off offset:2048
	global_load_dwordx2 v[168:169], v[152:153], off offset:3072
	global_load_dwordx2 v[170:171], v[152:153], off offset:1024
	v_add_u32_e32 v150, 32, v1
	v_mad_i64_i32 v[150:151], s[4:5], v150, s33, v[148:149]
	v_lshl_add_u64 v[150:151], v[150:151], 0, s[56:57]
	v_lshl_add_u64 v[150:151], v[150:151], 0, v[2:3]
	v_lshl_add_u64 v[152:153], v[150:151], 0, s[64:65]
	v_add_co_u32_e32 v150, vcc, s12, v150
	v_pk_mul_f32 v[74:75], v[74:75], v[154:155]
	s_nop 0
	v_addc_co_u32_e32 v151, vcc, 0, v151, vcc
	global_load_dwordx2 v[160:161], v[150:151], off
	global_load_dwordx2 v[158:159], v[152:153], off offset:2048
	global_load_dwordx2 v[154:155], v[152:153], off offset:3072
	global_load_dwordx2 v[156:157], v[152:153], off offset:1024
	v_add_u32_e32 v1, 48, v1
	v_mad_i64_i32 v[148:149], s[4:5], v1, s33, v[148:149]
	v_lshl_add_u64 v[148:149], v[148:149], 0, s[56:57]
	v_lshl_add_u64 v[2:3], v[148:149], 0, v[2:3]
	v_lshl_add_u64 v[148:149], v[2:3], 0, s[64:65]
	v_add_co_u32_e32 v2, vcc, s12, v2
	v_addc_co_u32_e32 v3, vcc, 0, v3, vcc
	global_load_dwordx2 v[152:153], v[2:3], off
	global_load_dwordx2 v[150:151], v[148:149], off offset:2048
	s_nop 0
	global_load_dwordx2 v[2:3], v[148:149], off offset:3072
	s_nop 0
	global_load_dwordx2 v[148:149], v[148:149], off offset:1024
	s_waitcnt vmcnt(4)
; __device__ __forceinline__ f32x4 un_unorm8(unsigned w) { return (f32x4){fmaxf((float)(w & 255u), 0.5f), fmaxf((float)((w >> 8) & 255u), 0.5f), fmaxf((float)((w >> 16) & 255u), 0.5f), fmaxf((float)(w >> 24), 0.5f)}; }
;     __device__ __forceinline__ void seam(f32x4 (&acc)[2][2][4][2], const Unit& u, int n, int wr, int wc, int fr, int fq) const {
;     ...
;             for (int m = 0; m < 4; ++m)
; #pragma unroll
;                 for (int bj = 0; bj < 2; ++bj) { const f32x4 a0 = un_unorm8(ga[m][bj].x), a1 = un_unorm8(ga[m][bj].y), b0 = un_unorm8(gb[m][bj].x), b1 = un_unorm8(gb[m][bj].y);
; #pragma unroll
;                     for (int j = 0; j < 4; ++j) { acc[ai][bj][m][0][j] *= a0[j] * __builtin_amdgcn_rcpf(b0[j]); acc[ai][bj][m][1][j] *= a1[j] * __builtin_amdgcn_rcpf(b1[j]); } }
	v_cvt_f32_ubyte0_e32 v1, v172
	v_max_f32_e32 v208, 0.5, v1
	v_cvt_f32_ubyte1_e32 v1, v172
	v_max_f32_e32 v209, 0.5, v1
	v_cvt_f32_ubyte2_e32 v1, v172
	v_max_f32_e32 v210, 0.5, v1
	v_cvt_f32_ubyte3_e32 v1, v172
	v_max_f32_e32 v211, 0.5, v1
	v_cvt_f32_ubyte0_e32 v1, v173
	v_max_f32_e32 v212, 0.5, v1
	v_cvt_f32_ubyte1_e32 v1, v173
	v_max_f32_e32 v213, 0.5, v1
	v_cvt_f32_ubyte2_e32 v1, v173
	v_max_f32_e32 v172, 0.5, v1
	v_cvt_f32_ubyte3_e32 v1, v173
	v_cvt_f32_ubyte1_e32 v214, v174
	v_max_f32_e32 v173, 0.5, v1
	v_cvt_f32_ubyte0_e32 v1, v174
	v_max_f32_e32 v215, 0.5, v214
	v_cvt_f32_ubyte2_e32 v214, v174
	v_cvt_f32_ubyte3_e32 v174, v174
	v_max_f32_e32 v217, 0.5, v174
	v_cvt_f32_ubyte0_e32 v174, v175
	v_max_f32_e32 v216, 0.5, v214
	v_max_f32_e32 v214, 0.5, v174
	v_cvt_f32_ubyte1_e32 v174, v175
	v_max_f32_e32 v218, 0.5, v174
	v_cvt_f32_ubyte2_e32 v174, v175
	v_max_f32_e32 v219, 0.5, v174
	v_cvt_f32_ubyte3_e32 v174, v175
	v_max_f32_e32 v220, 0.5, v174
	v_max_f32_e32 v1, 0.5, v1
	v_rcp_f32_e32 v175, v215
	v_rcp_f32_e32 v215, v218
	v_rcp_f32_e32 v218, v219
	v_rcp_f32_e32 v219, v220
	v_rcp_f32_e32 v174, v1
	v_rcp_f32_e32 v214, v214
	v_rcp_f32_e32 v216, v216
	v_rcp_f32_e32 v217, v217
	v_pk_mul_f32 v[172:173], v[172:173], v[218:219]
	v_cvt_f32_ubyte0_e32 v1, v178
	v_pk_mul_f32 v[174:175], v[208:209], v[174:175]
	v_pk_mul_f32 v[62:63], v[62:63], v[172:173]
	v_max_f32_e32 v172, 0.5, v1
	v_cvt_f32_ubyte1_e32 v1, v178
	v_pk_mul_f32 v[64:65], v[64:65], v[174:175]
	v_pk_mul_f32 v[174:175], v[212:213], v[214:215]
	v_max_f32_e32 v173, 0.5, v1
	v_cvt_f32_ubyte2_e32 v1, v178
	v_pk_mul_f32 v[60:61], v[60:61], v[174:175]
	v_max_f32_e32 v174, 0.5, v1
	v_cvt_f32_ubyte3_e32 v1, v178
	v_pk_mul_f32 v[208:209], v[210:211], v[216:217]
	v_max_f32_e32 v175, 0.5, v1
	v_cvt_f32_ubyte0_e32 v1, v179
	v_pk_mul_f32 v[66:67], v[66:67], v[208:209]
	v_max_f32_e32 v208, 0.5, v1
	v_cvt_f32_ubyte1_e32 v1, v179
	v_max_f32_e32 v209, 0.5, v1
	v_cvt_f32_ubyte2_e32 v1, v179
	v_max_f32_e32 v178, 0.5, v1
	v_cvt_f32_ubyte3_e32 v1, v179
	v_cvt_f32_ubyte1_e32 v210, v176
	v_max_f32_e32 v179, 0.5, v1
	v_cvt_f32_ubyte0_e32 v1, v176
	v_max_f32_e32 v211, 0.5, v210
	v_cvt_f32_ubyte2_e32 v210, v176
	v_cvt_f32_ubyte3_e32 v176, v176
	v_max_f32_e32 v213, 0.5, v176
	v_cvt_f32_ubyte0_e32 v176, v177
	v_max_f32_e32 v212, 0.5, v210
	v_max_f32_e32 v210, 0.5, v176
	v_cvt_f32_ubyte1_e32 v176, v177
	v_max_f32_e32 v214, 0.5, v176
	v_cvt_f32_ubyte2_e32 v176, v177
	v_max_f32_e32 v1, 0.5, v1
	v_max_f32_e32 v215, 0.5, v176
	v_cvt_f32_ubyte3_e32 v176, v177
	v_max_f32_e32 v216, 0.5, v176
	v_rcp_f32_e32 v176, v1
	v_rcp_f32_e32 v177, v211
	v_rcp_f32_e32 v210, v210
	v_rcp_f32_e32 v211, v214
	v_rcp_f32_e32 v212, v212
	v_rcp_f32_e32 v213, v213
	v_rcp_f32_e32 v214, v215
	v_rcp_f32_e32 v215, v216
	v_pk_mul_f32 v[172:173], v[172:173], v[176:177]
	v_cvt_f32_ubyte0_e32 v1, v184
	v_pk_mul_f32 v[56:57], v[56:57], v[172:173]
	v_pk_mul_f32 v[172:173], v[208:209], v[210:211]
	v_pk_mul_f32 v[174:175], v[174:175], v[212:213]
	v_pk_mul_f32 v[52:53], v[52:53], v[172:173]
	v_max_f32_e32 v172, 0.5, v1
	v_cvt_f32_ubyte1_e32 v1, v184
	v_pk_mul_f32 v[58:59], v[58:59], v[174:175]
	v_pk_mul_f32 v[174:175], v[178:179], v[214:215]
	v_max_f32_e32 v173, 0.5, v1
	v_cvt_f32_ubyte2_e32 v1, v184
	v_pk_mul_f32 v[54:55], v[54:55], v[174:175]
	v_max_f32_e32 v174, 0.5, v1
	v_cvt_f32_ubyte3_e32 v1, v184
	v_max_f32_e32 v175, 0.5, v1
	v_cvt_f32_ubyte0_e32 v1, v185
	v_max_f32_e32 v176, 0.5, v1
	v_cvt_f32_ubyte1_e32 v1, v185
	v_max_f32_e32 v177, 0.5, v1
	v_cvt_f32_ubyte2_e32 v1, v185
	v_cvt_f32_ubyte1_e32 v184, v186
	v_max_f32_e32 v178, 0.5, v1
	v_cvt_f32_ubyte3_e32 v1, v185
	v_max_f32_e32 v185, 0.5, v184
	v_cvt_f32_ubyte2_e32 v184, v186
	v_max_f32_e32 v208, 0.5, v184
	v_cvt_f32_ubyte3_e32 v184, v186
	v_max_f32_e32 v209, 0.5, v184
	v_cvt_f32_ubyte0_e32 v184, v187
	v_max_f32_e32 v179, 0.5, v1
	v_cvt_f32_ubyte0_e32 v1, v186
	v_max_f32_e32 v186, 0.5, v184
	v_cvt_f32_ubyte1_e32 v184, v187
	v_max_f32_e32 v210, 0.5, v184
	v_cvt_f32_ubyte2_e32 v184, v187
	v_max_f32_e32 v1, 0.5, v1
	v_max_f32_e32 v211, 0.5, v184
	v_cvt_f32_ubyte3_e32 v184, v187
	v_max_f32_e32 v212, 0.5, v184
	v_rcp_f32_e32 v184, v1
	v_rcp_f32_e32 v185, v185
	v_rcp_f32_e32 v186, v186
	v_rcp_f32_e32 v187, v210
	v_rcp_f32_e32 v208, v208
	v_rcp_f32_e32 v209, v209
	v_rcp_f32_e32 v210, v211
	v_rcp_f32_e32 v211, v212
	v_pk_mul_f32 v[172:173], v[172:173], v[184:185]
	v_cvt_f32_ubyte0_e32 v1, v170
	v_pk_mul_f32 v[48:49], v[48:49], v[172:173]
	v_pk_mul_f32 v[172:173], v[176:177], v[186:187]
	v_pk_mul_f32 v[174:175], v[174:175], v[208:209]
	v_pk_mul_f32 v[44:45], v[44:45], v[172:173]
	v_max_f32_e32 v172, 0.5, v1
	v_cvt_f32_ubyte1_e32 v1, v170
	v_pk_mul_f32 v[50:51], v[50:51], v[174:175]
	v_pk_mul_f32 v[174:175], v[178:179], v[210:211]
	v_max_f32_e32 v173, 0.5, v1
	v_cvt_f32_ubyte2_e32 v1, v170
	v_pk_mul_f32 v[46:47], v[46:47], v[174:175]
	v_max_f32_e32 v174, 0.5, v1
	v_cvt_f32_ubyte3_e32 v1, v170
	v_max_f32_e32 v175, 0.5, v1
	v_cvt_f32_ubyte0_e32 v1, v171
	v_max_f32_e32 v176, 0.5, v1
	v_cvt_f32_ubyte1_e32 v1, v171
	v_max_f32_e32 v177, 0.5, v1
	v_cvt_f32_ubyte2_e32 v1, v171
	v_max_f32_e32 v170, 0.5, v1
	v_cvt_f32_ubyte3_e32 v1, v171
	v_cvt_f32_ubyte1_e32 v178, v168
	v_max_f32_e32 v171, 0.5, v1
	v_cvt_f32_ubyte0_e32 v1, v168
	v_max_f32_e32 v179, 0.5, v178
	v_cvt_f32_ubyte2_e32 v178, v168
	v_cvt_f32_ubyte3_e32 v168, v168
	v_max_f32_e32 v185, 0.5, v168
	v_cvt_f32_ubyte0_e32 v168, v169
	v_max_f32_e32 v184, 0.5, v178
	v_max_f32_e32 v178, 0.5, v168
	v_cvt_f32_ubyte1_e32 v168, v169
	v_max_f32_e32 v186, 0.5, v168
	v_cvt_f32_ubyte2_e32 v168, v169
	v_max_f32_e32 v1, 0.5, v1
	v_max_f32_e32 v187, 0.5, v168
; __device__ __forceinline__ f32x4 un_unorm8(unsigned w) { return (f32x4){fmaxf((float)(w & 255u), 0.5f), fmaxf((float)((w >> 8) & 255u), 0.5f), fmaxf((float)((w >> 16) & 255u), 0.5f), fmaxf((float)(w >> 24), 0.5f)}; }
;     __device__ __forceinline__ void seam(f32x4 (&acc)[2][2][4][2], const Unit& u, int n, int wr, int wc, int fr, int fq) const {
;     ...
;             for (int m = 0; m < 4; ++m)
; #pragma unroll
;                 for (int bj = 0; bj < 2; ++bj) { const f32x4 a0 = un_unorm8(ga[m][bj].x), a1 = un_unorm8(ga[m][bj].y), b0 = un_unorm8(gb[m][bj].x), b1 = un_unorm8(gb[m][bj].y);
; #pragma unroll
;                     for (int j = 0; j < 4; ++j) { acc[ai][bj][m][0][j] *= a0[j] * __builtin_amdgcn_rcpf(b0[j]); acc[ai][bj][m][1][j] *= a1[j] * __builtin_amdgcn_rcpf(b1[j]); } }
;             asm volatile("" ::: "memory");
;         }
	v_cvt_f32_ubyte3_e32 v168, v169
	v_max_f32_e32 v208, 0.5, v168
	v_rcp_f32_e32 v168, v1
	v_rcp_f32_e32 v169, v179
	v_rcp_f32_e32 v178, v178
	v_rcp_f32_e32 v179, v186
	v_rcp_f32_e32 v186, v187
	v_rcp_f32_e32 v187, v208
	v_pk_mul_f32 v[168:169], v[172:173], v[168:169]
	v_rcp_f32_e32 v184, v184
	v_rcp_f32_e32 v185, v185
	v_pk_mul_f32 v[40:41], v[40:41], v[168:169]
	v_pk_mul_f32 v[168:169], v[176:177], v[178:179]
	v_cvt_f32_ubyte0_e32 v1, v160
	v_pk_mul_f32 v[36:37], v[36:37], v[168:169]
	v_max_f32_e32 v168, 0.5, v1
	v_cvt_f32_ubyte1_e32 v1, v160
	v_pk_mul_f32 v[170:171], v[170:171], v[186:187]
	v_max_f32_e32 v169, 0.5, v1
	v_cvt_f32_ubyte2_e32 v1, v160
	v_pk_mul_f32 v[38:39], v[38:39], v[170:171]
	v_max_f32_e32 v170, 0.5, v1
	v_cvt_f32_ubyte3_e32 v1, v160
	v_pk_mul_f32 v[172:173], v[174:175], v[184:185]
	v_max_f32_e32 v171, 0.5, v1
	v_cvt_f32_ubyte0_e32 v1, v161
	v_pk_mul_f32 v[42:43], v[42:43], v[172:173]
	v_max_f32_e32 v172, 0.5, v1
	v_cvt_f32_ubyte1_e32 v1, v161
	v_max_f32_e32 v173, 0.5, v1
	v_cvt_f32_ubyte2_e32 v1, v161
	v_max_f32_e32 v160, 0.5, v1
	v_cvt_f32_ubyte3_e32 v1, v161
	v_cvt_f32_ubyte1_e32 v174, v158
	v_max_f32_e32 v161, 0.5, v1
	v_cvt_f32_ubyte0_e32 v1, v158
	v_max_f32_e32 v175, 0.5, v174
	v_cvt_f32_ubyte2_e32 v174, v158
	v_cvt_f32_ubyte3_e32 v158, v158
	v_max_f32_e32 v177, 0.5, v158
	v_cvt_f32_ubyte0_e32 v158, v159
	v_max_f32_e32 v176, 0.5, v174
	v_max_f32_e32 v174, 0.5, v158
	v_cvt_f32_ubyte1_e32 v158, v159
	v_max_f32_e32 v178, 0.5, v158
	v_cvt_f32_ubyte2_e32 v158, v159
	v_max_f32_e32 v1, 0.5, v1
	v_max_f32_e32 v179, 0.5, v158
	v_cvt_f32_ubyte3_e32 v158, v159
	v_max_f32_e32 v184, 0.5, v158
	v_rcp_f32_e32 v158, v1
	v_rcp_f32_e32 v159, v175
	v_rcp_f32_e32 v174, v174
	v_rcp_f32_e32 v175, v178
	v_rcp_f32_e32 v178, v179
	v_rcp_f32_e32 v179, v184
	v_pk_mul_f32 v[158:159], v[168:169], v[158:159]
	v_rcp_f32_e32 v176, v176
	v_rcp_f32_e32 v177, v177
	v_pk_mul_f32 v[32:33], v[32:33], v[158:159]
	v_pk_mul_f32 v[158:159], v[172:173], v[174:175]
	v_cvt_f32_ubyte0_e32 v1, v156
	v_pk_mul_f32 v[28:29], v[28:29], v[158:159]
	v_max_f32_e32 v158, 0.5, v1
	v_cvt_f32_ubyte1_e32 v1, v156
	v_pk_mul_f32 v[160:161], v[160:161], v[178:179]
	v_max_f32_e32 v159, 0.5, v1
	v_cvt_f32_ubyte2_e32 v1, v156
	v_pk_mul_f32 v[30:31], v[30:31], v[160:161]
	v_max_f32_e32 v160, 0.5, v1
	v_cvt_f32_ubyte3_e32 v1, v156
	v_pk_mul_f32 v[168:169], v[170:171], v[176:177]
	v_max_f32_e32 v161, 0.5, v1
	v_cvt_f32_ubyte0_e32 v1, v157
	v_pk_mul_f32 v[34:35], v[34:35], v[168:169]
	v_max_f32_e32 v168, 0.5, v1
	v_cvt_f32_ubyte1_e32 v1, v157
	v_max_f32_e32 v169, 0.5, v1
	v_cvt_f32_ubyte2_e32 v1, v157
	v_max_f32_e32 v156, 0.5, v1
	v_cvt_f32_ubyte3_e32 v1, v157
	v_cvt_f32_ubyte1_e32 v170, v154
	v_max_f32_e32 v157, 0.5, v1
	v_cvt_f32_ubyte0_e32 v1, v154
	v_max_f32_e32 v171, 0.5, v170
	v_cvt_f32_ubyte2_e32 v170, v154
	v_cvt_f32_ubyte3_e32 v154, v154
	v_max_f32_e32 v173, 0.5, v154
	v_cvt_f32_ubyte0_e32 v154, v155
	v_max_f32_e32 v172, 0.5, v170
	v_max_f32_e32 v170, 0.5, v154
	v_cvt_f32_ubyte1_e32 v154, v155
	v_max_f32_e32 v174, 0.5, v154
	v_cvt_f32_ubyte2_e32 v154, v155
	v_max_f32_e32 v1, 0.5, v1
	v_max_f32_e32 v175, 0.5, v154
	v_cvt_f32_ubyte3_e32 v154, v155
	v_max_f32_e32 v176, 0.5, v154
	v_rcp_f32_e32 v154, v1
	v_rcp_f32_e32 v155, v171
	v_rcp_f32_e32 v170, v170
	v_rcp_f32_e32 v171, v174
	v_rcp_f32_e32 v174, v175
	v_rcp_f32_e32 v175, v176
	v_pk_mul_f32 v[154:155], v[158:159], v[154:155]
	v_rcp_f32_e32 v172, v172
	v_rcp_f32_e32 v173, v173
	v_pk_mul_f32 v[24:25], v[24:25], v[154:155]
	v_pk_mul_f32 v[154:155], v[168:169], v[170:171]
	s_waitcnt vmcnt(0)
	v_cvt_f32_ubyte0_e32 v1, v152
	v_pk_mul_f32 v[20:21], v[20:21], v[154:155]
	v_max_f32_e32 v154, 0.5, v1
	v_cvt_f32_ubyte1_e32 v1, v152
	v_pk_mul_f32 v[156:157], v[156:157], v[174:175]
	v_max_f32_e32 v155, 0.5, v1
	v_cvt_f32_ubyte2_e32 v1, v152
	v_pk_mul_f32 v[22:23], v[22:23], v[156:157]
	v_max_f32_e32 v156, 0.5, v1
	v_cvt_f32_ubyte3_e32 v1, v152
	v_pk_mul_f32 v[158:159], v[160:161], v[172:173]
	v_max_f32_e32 v157, 0.5, v1
	v_cvt_f32_ubyte0_e32 v1, v153
	v_pk_mul_f32 v[26:27], v[26:27], v[158:159]
	v_max_f32_e32 v158, 0.5, v1
	v_cvt_f32_ubyte1_e32 v1, v153
	v_max_f32_e32 v159, 0.5, v1
	v_cvt_f32_ubyte2_e32 v1, v153
	v_max_f32_e32 v152, 0.5, v1
	v_cvt_f32_ubyte3_e32 v1, v153
	v_cvt_f32_ubyte1_e32 v160, v150
	v_max_f32_e32 v153, 0.5, v1
	v_cvt_f32_ubyte0_e32 v1, v150
	v_max_f32_e32 v161, 0.5, v160
	v_cvt_f32_ubyte2_e32 v160, v150
	v_cvt_f32_ubyte3_e32 v150, v150
	v_max_f32_e32 v169, 0.5, v150
	v_cvt_f32_ubyte0_e32 v150, v151
	v_max_f32_e32 v168, 0.5, v160
	v_max_f32_e32 v160, 0.5, v150
	v_cvt_f32_ubyte1_e32 v150, v151
	v_max_f32_e32 v170, 0.5, v150
	v_cvt_f32_ubyte2_e32 v150, v151
	v_max_f32_e32 v1, 0.5, v1
	v_max_f32_e32 v171, 0.5, v150
	v_cvt_f32_ubyte3_e32 v150, v151
	v_max_f32_e32 v172, 0.5, v150
	v_rcp_f32_e32 v150, v1
	v_rcp_f32_e32 v151, v161
	v_rcp_f32_e32 v160, v160
	v_rcp_f32_e32 v161, v170
	v_rcp_f32_e32 v170, v171
	v_rcp_f32_e32 v171, v172
	v_pk_mul_f32 v[150:151], v[154:155], v[150:151]
	v_rcp_f32_e32 v168, v168
	v_rcp_f32_e32 v169, v169
	v_pk_mul_f32 v[16:17], v[16:17], v[150:151]
	v_pk_mul_f32 v[150:151], v[158:159], v[160:161]
	v_cvt_f32_ubyte0_e32 v1, v148
	v_pk_mul_f32 v[12:13], v[12:13], v[150:151]
	v_max_f32_e32 v150, 0.5, v1
	v_cvt_f32_ubyte1_e32 v1, v148
	v_pk_mul_f32 v[152:153], v[152:153], v[170:171]
	v_max_f32_e32 v151, 0.5, v1
	v_cvt_f32_ubyte2_e32 v1, v148
	v_pk_mul_f32 v[14:15], v[14:15], v[152:153]
	v_max_f32_e32 v152, 0.5, v1
	v_cvt_f32_ubyte3_e32 v1, v148
	v_pk_mul_f32 v[154:155], v[156:157], v[168:169]
	v_max_f32_e32 v153, 0.5, v1
	v_cvt_f32_ubyte0_e32 v1, v149
	v_pk_mul_f32 v[18:19], v[18:19], v[154:155]
	v_max_f32_e32 v154, 0.5, v1
	v_cvt_f32_ubyte1_e32 v1, v149
	v_max_f32_e32 v155, 0.5, v1
	v_cvt_f32_ubyte2_e32 v1, v149
	v_max_f32_e32 v148, 0.5, v1
	v_cvt_f32_ubyte3_e32 v1, v149
	v_cvt_f32_ubyte1_e32 v156, v2
	v_max_f32_e32 v149, 0.5, v1
	v_cvt_f32_ubyte0_e32 v1, v2
	v_max_f32_e32 v157, 0.5, v156
	v_cvt_f32_ubyte2_e32 v156, v2
	v_cvt_f32_ubyte3_e32 v2, v2
	v_max_f32_e32 v159, 0.5, v2
	v_cvt_f32_ubyte0_e32 v2, v3
	v_max_f32_e32 v158, 0.5, v156
	v_max_f32_e32 v156, 0.5, v2
	v_cvt_f32_ubyte1_e32 v2, v3
	v_max_f32_e32 v160, 0.5, v2
	v_cvt_f32_ubyte2_e32 v2, v3
	v_max_f32_e32 v1, 0.5, v1
	v_max_f32_e32 v161, 0.5, v2
	v_cvt_f32_ubyte3_e32 v2, v3
	v_max_f32_e32 v168, 0.5, v2
	v_rcp_f32_e32 v2, v1
	v_rcp_f32_e32 v3, v157
	v_rcp_f32_e32 v156, v156
	v_rcp_f32_e32 v158, v158
	v_rcp_f32_e32 v159, v159
	v_rcp_f32_e32 v157, v160
	v_rcp_f32_e32 v160, v161
	v_rcp_f32_e32 v161, v168
	v_pk_mul_f32 v[2:3], v[150:151], v[2:3]
	v_pk_mul_f32 v[150:151], v[152:153], v[158:159]
	v_pk_mul_f32 v[8:9], v[8:9], v[2:3]
	v_pk_mul_f32 v[2:3], v[154:155], v[156:157]
	v_pk_mul_f32 v[148:149], v[148:149], v[160:161]
	v_pk_mul_f32 v[10:11], v[10:11], v[150:151]
	v_pk_mul_f32 v[6:7], v[6:7], v[148:149]
	v_pk_mul_f32 v[4:5], v[4:5], v[2:3]
	s_cmp_eq_u32 s56, 0
	s_cbranch_scc0 .Lspre_e
;     __device__ __forceinline__ void seam(f32x4 (&acc)[2][2][4][2], const Unit& u, int n, int wr, int wc, int fr, int fq) const {
;     ...
;                 for (int bj = 0; bj < 2; ++bj) { const int row = u.pm * 256 + ai * 128 + wr * 64 + m * 16 + fr, col = u.pn * 256 + bj * 128 + wc * 32 + 8 * fq;
;                     const unsigned char* gp = (const unsigned char*)P + (size_t)row * ROWB + GATE_B0 + n * DM + col; ga[m][bj] = *(const u32x2*)gp; gb[m][bj] = *(const u32x2*)(gp + DM); }
;     __device__ __forceinline__ void operator()(f32x4 (&acc)[2][2][4][2], const Unit& u, int wr, int wc, int fr, int fq) const {
;     ...
;                 for (int bj = 0; bj < 2; ++bj) { const int row = u.pm * 256 + ai * 128 + wr * 64 + m * 16 + fr, col = u.pn * 256 + bj * 128 + wc * 32 + 8 * fq;
;                     gg[m][bj] = *(const u32x2*)((const unsigned char*)P + (size_t)row * ROWB + GATE_B0 + 2 * DM + col); }
	s_lshr_b32 s98, s42, 7
	s_bfe_u32 s99, s42, 0x10006
	s_or_b32 s98, s98, s99
	s_add_i32 s98, s98, s8
	s_add_i32 s98, s98, s20
	s_mul_i32 s98, s98, 0x4800
	s_add_u32 s98, s68, s98
	s_addc_u32 s99, s69, 0
	s_add_u32 s98, s98, 0x3800
	s_addc_u32 s99, s99, 0
	global_load_dwordx2 v[192:193], v254, s[98:99] offset:2048
	global_load_dwordx2 v[194:195], v254, s[98:99]
	global_load_dwordx2 v[196:197], v254, s[98:99] offset:3072
	global_load_dwordx2 v[198:199], v254, s[98:99] offset:1024
	s_add_u32 s98, s98, 0x48000
	s_addc_u32 s99, s99, 0
	global_load_dwordx2 v[200:201], v254, s[98:99] offset:2048
	global_load_dwordx2 v[202:203], v254, s[98:99]
	global_load_dwordx2 v[204:205], v254, s[98:99] offset:3072
	global_load_dwordx2 v[206:207], v254, s[98:99] offset:1024
	s_branch .Lspre_x
.Lspre_e:
	s_lshr_b32 s98, s42, 7
	s_bfe_u32 s99, s42, 0x10006
	s_or_b32 s98, s98, s99
	s_add_i32 s98, s98, s8
	s_add_i32 s98, s98, s20
	s_mul_i32 s98, s98, 0x4800
	s_add_u32 s98, s68, s98
	s_addc_u32 s99, s69, 0
	s_add_u32 s98, s98, 0x4000
	s_addc_u32 s99, s99, 0
	global_load_dwordx2 v[192:193], v254, s[98:99]
	global_load_dwordx2 v[194:195], v254, s[98:99] offset:1024
	s_add_u32 s98, s98, 0x48000
	s_addc_u32 s99, s99, 0
	global_load_dwordx2 v[196:197], v254, s[98:99]
	global_load_dwordx2 v[198:199], v254, s[98:99] offset:1024
	s_add_u32 s98, s98, 0x48000
	s_addc_u32 s99, s99, 0
	global_load_dwordx2 v[200:201], v254, s[98:99]
	global_load_dwordx2 v[202:203], v254, s[98:99] offset:1024
	s_add_u32 s98, s98, 0x48000
	s_addc_u32 s99, s99, 0
	global_load_dwordx2 v[204:205], v254, s[98:99]
	global_load_dwordx2 v[206:207], v254, s[98:99] offset:1024
.Lspre_x:
	s_andn2_b64 vcc, exec, s[44:45]
	s_cbranch_vccnz .Lsm_b
	s_barrier
